# grid barrier: non-last WGs poll the top-level generation word directly (one hop less per barrier); on the best stack
# speedup vs baseline: 1.0017x; 1.0017x over previous
.LBB0_133:
	s_or_b64 exec, exec, s[8:9]
	v_cvt_f32_u32_e32 v4, v2
	s_waitcnt vmcnt(0)
	v_readfirstlane_b32 s3, v3
	v_sub_u32_e32 v3, 0, v2
	v_rcp_iflag_f32_e32 v4, v4
	v_add_u32_e32 v5, s3, v1
	v_mul_f32_e32 v4, 0x4f7ffffe, v4
	v_cvt_u32_f32_e32 v4, v4
	v_mul_lo_u32 v1, v3, v4
	v_mul_hi_u32 v1, v4, v1
	v_add_u32_e32 v1, v4, v1
	v_mul_hi_u32 v1, v5, v1
	v_mul_lo_u32 v3, v1, v2
	v_sub_u32_e32 v3, v5, v3
	v_add_u32_e32 v4, 1, v1
	v_cmp_ge_u32_e32 vcc, v3, v2
	s_nop 1
	v_cndmask_b32_e32 v1, v1, v4, vcc
	v_sub_u32_e32 v4, v3, v2
	v_cndmask_b32_e32 v3, v3, v4, vcc
	v_add_u32_e32 v4, 1, v1
	v_cmp_ge_u32_e32 vcc, v3, v2
	v_add_u32_e32 v3, 1, v5
	s_nop 0
	v_cndmask_b32_e32 v1, v1, v4, vcc
	v_mul_lo_u32 v4, v2, v1
	v_add_u32_e32 v2, v4, v2
	v_cmp_ne_u32_e32 vcc, v3, v2
	s_and_saveexec_b64 s[6:7], vcc
	s_xor_b64 s[6:7], exec, s[6:7]
	s_cbranch_execz .LBB0_147
	s_waitcnt lgkmcnt(0)
	v_mov_b32_e32 v0, 0x43500
	global_load_dword v0, v0, s[68:69] sc1
	s_add_u32 s12, s68, 0x43500
	s_addc_u32 s13, s69, 0
	s_waitcnt vmcnt(0)
	v_cmp_eq_u32_e32 vcc, v0, v1
	s_and_saveexec_b64 s[8:9], vcc
	s_cbranch_execz .LBB0_146
	s_add_u32 s10, s68, 0x40200
	s_addc_u32 s11, s69, 0
	s_mov_b32 s3, 1
	s_mov_b64 s[14:15], 0
	v_mov_b32_e32 v0, 0
	s_branch .LBB0_137

.LBB0_399:
	s_or_b64 exec, exec, s[8:9]
	v_cvt_f32_u32_e32 v4, v2
	s_waitcnt vmcnt(0)
	v_readfirstlane_b32 s3, v3
	v_sub_u32_e32 v3, 0, v2
	v_rcp_iflag_f32_e32 v4, v4
	v_add_u32_e32 v5, s3, v1
	v_mul_f32_e32 v4, 0x4f7ffffe, v4
	v_cvt_u32_f32_e32 v4, v4
	v_mul_lo_u32 v1, v3, v4
	v_mul_hi_u32 v1, v4, v1
	v_add_u32_e32 v1, v4, v1
	v_mul_hi_u32 v1, v5, v1
	v_mul_lo_u32 v3, v1, v2
	v_sub_u32_e32 v3, v5, v3
	v_add_u32_e32 v4, 1, v1
	v_cmp_ge_u32_e32 vcc, v3, v2
	s_nop 1
	v_cndmask_b32_e32 v1, v1, v4, vcc
	v_sub_u32_e32 v4, v3, v2
	v_cndmask_b32_e32 v3, v3, v4, vcc
	v_add_u32_e32 v4, 1, v1
	v_cmp_ge_u32_e32 vcc, v3, v2
	v_add_u32_e32 v3, 1, v5
	s_nop 0
	v_cndmask_b32_e32 v1, v1, v4, vcc
	v_mul_lo_u32 v4, v2, v1
	v_add_u32_e32 v2, v4, v2
	v_cmp_ne_u32_e32 vcc, v3, v2
	s_and_saveexec_b64 s[6:7], vcc
	s_xor_b64 s[6:7], exec, s[6:7]
	s_cbranch_execz .LBB0_413
	s_waitcnt lgkmcnt(0)
	v_mov_b32_e32 v0, 0x43500
	global_load_dword v0, v0, s[68:69] sc1
	s_add_u32 s14, s68, 0x43500
	s_addc_u32 s15, s69, 0
	s_waitcnt vmcnt(0)
	v_cmp_eq_u32_e32 vcc, v0, v1
	s_and_saveexec_b64 s[8:9], vcc
	s_cbranch_execz .LBB0_412
	s_add_u32 s10, s68, 0x40200
	s_addc_u32 s11, s69, 0
	s_mov_b32 s3, 1
	s_mov_b64 s[16:17], 0
	v_mov_b32_e32 v0, 0
	s_branch .LBB0_403

.LBB0_582:
	s_or_b64 exec, exec, s[8:9]
	v_cvt_f32_u32_e32 v4, v2
	s_waitcnt vmcnt(0)
	v_readfirstlane_b32 s4, v3
	v_sub_u32_e32 v3, 0, v2
	v_rcp_iflag_f32_e32 v4, v4
	v_add_u32_e32 v5, s4, v1
	v_mul_f32_e32 v4, 0x4f7ffffe, v4
	v_cvt_u32_f32_e32 v4, v4
	v_mul_lo_u32 v1, v3, v4
	v_mul_hi_u32 v1, v4, v1
	v_add_u32_e32 v1, v4, v1
	v_mul_hi_u32 v1, v5, v1
	v_mul_lo_u32 v3, v1, v2
	v_sub_u32_e32 v3, v5, v3
	v_add_u32_e32 v4, 1, v1
	v_cmp_ge_u32_e32 vcc, v3, v2
	s_nop 1
	v_cndmask_b32_e32 v1, v1, v4, vcc
	v_sub_u32_e32 v4, v3, v2
	v_cndmask_b32_e32 v3, v3, v4, vcc
	v_add_u32_e32 v4, 1, v1
	v_cmp_ge_u32_e32 vcc, v3, v2
	v_add_u32_e32 v3, 1, v5
	s_nop 0
	v_cndmask_b32_e32 v1, v1, v4, vcc
	v_mul_lo_u32 v4, v2, v1
	v_add_u32_e32 v2, v4, v2
	v_cmp_ne_u32_e32 vcc, v3, v2
	s_and_saveexec_b64 s[4:5], vcc
	s_xor_b64 s[4:5], exec, s[4:5]
	s_cbranch_execz .LBB0_596
	s_waitcnt lgkmcnt(0)
	v_mov_b32_e32 v0, 0x43500
	global_load_dword v0, v0, s[68:69] sc1
	s_add_u32 s12, s68, 0x43500
	s_addc_u32 s13, s69, 0
	s_waitcnt vmcnt(0)
	v_cmp_eq_u32_e32 vcc, v0, v1
	s_and_saveexec_b64 s[8:9], vcc
	s_cbranch_execz .LBB0_595
	s_add_u32 s10, s68, 0x40200
	s_addc_u32 s11, s69, 0
	s_mov_b32 s24, 1
	s_mov_b64 s[14:15], 0
	v_mov_b32_e32 v0, 0
	s_branch .LBB0_586
